# FFN-up: row sum-of-squares loads for the epilogue rinv issued at the unit head (hidden under the K-loop)
# baseline (speedup 1.0000x reference)
; #define LAS __attribute__((address_space(3)))
; __device__ __forceinline__ int lane_id_hw() { int l; asm volatile("v_mbcnt_lo_u32_b32 %0, -1, 0\n\tv_mbcnt_hi_u32_b32 %0, -1, %0" : "=v"(l)); return l; }
; __device__ __forceinline__ float sum16(const float* p) { const f32x4 a = *(const f32x4*)p, b = *(const f32x4*)(p + 4), c = *(const f32x4*)(p + 8), d = *(const f32x4*)(p + 12);
;     __device__ __forceinline__ void operator()(f32x4 (&acc)[2][2][4][2], const Unit& u, int wr, int wc, int fr, int fq, int next_pn) const {
;     ...
;         if (*(volatile LAS int*)(R + 256) != u.pm) {
;             const int wv = 4 * wr + wc, l_ = lane_id_hw(); if (wv < 4) { const int r = wv * 64 + l_; R[r] = rsqrtf(sum16(ss + (size_t)(u.pm * BM + r) * 16) * (1.0f / 1024.0f) + EPS); }
.LBB0_644:
	s_and_b64 vcc, exec, s[28:29]
	s_cbranch_vccz .Lffn_nopf
	s_add_i32 s98, 0, 0x22000
	v_mov_b32_e32 v216, s98
	ds_read_b32 v216, v216
	s_waitcnt lgkmcnt(0)
	v_readfirstlane_b32 s98, v216
	s_cmp_eq_u32 s98, s89
	s_cbranch_scc1 .Lffn_nopf
	v_mbcnt_lo_u32_b32 v216, -1, 0
	v_mbcnt_hi_u32_b32 v216, -1, v216
	v_add_u32_e32 v216, s69, v216
	v_lshl_add_u32 v216, s89, 8, v216
	v_ashrrev_i32_e32 v217, 31, v216
	v_lshlrev_b64 v[216:217], 6, v[216:217]
	v_readlane_b32 s98, v254, 51
	v_readlane_b32 s99, v254, 52
	s_nop 1
	v_lshl_add_u64 v[216:217], s[98:99], 0, v[216:217]
	global_load_dwordx4 v[228:231], v[216:217], off
	global_load_dwordx4 v[232:235], v[216:217], off offset:32
	global_load_dwordx4 v[236:239], v[216:217], off offset:16
	global_load_dwordx4 v[196:199], v[216:217], off offset:48

; #define PG8_STAGE(bufoff, gbase, voff) do { _Pragma("unroll") for (int _i = 0; _i < 2; ++_i) \
;         __builtin_amdgcn_global_load_lds((const unsigned*)((const char*)(gbase) + (voff)[_i]), (LAS unsigned*)(lds + (bufoff) + ldsw + _i * 8192), 16, 0, 0); } while (0)
; #define PG8_LDA(dst, b, h) do { _Pragma("unroll") for (int m = 0; m < 4; ++m) _Pragma("unroll") for (int k = 0; k < 2; ++k) dst[m][k] = *(const LAS bf16x8*)(lds + PG8_SA(b, h) + aoff + m * 2048 + k * 1024); } while (0)
; #define PG8_LDB(dst, b, h) do { _Pragma("unroll") for (int n = 0; n < 2; ++n) _Pragma("unroll") for (int k = 0; k < 2; ++k) dst[n][k] = *(const LAS bf16x8*)(lds + PG8_SB(b, h) + boff + n * 2048 + k * 1024); } while (0)
; #define PG8_MMA(ai, bj, At, Bt) do { __builtin_amdgcn_s_setprio(1); _Pragma("unroll") for (int m = 0; m < 4; ++m) _Pragma("unroll") for (int n = 0; n < 2; ++n) _Pragma("unroll") for (int k = 0; k < 2; ++k) \
;         acc[ai][bj][m][n] = __builtin_amdgcn_mfma_f32_16x16x32_bf16(Bt[n][k], At[m][k], acc[ai][bj][m][n], 0, 0, 0); __builtin_amdgcn_s_setprio(0); } while (0)
; #define PG8_WAIT_V(n) asm volatile("s_waitcnt vmcnt(" #n ")" ::: "memory")
; #define PG8_BAR __builtin_amdgcn_s_barrier()
; template <class Epi>
; __device__ __forceinline__ void gemm_phase(LAS unsigned char* lds, const Gemm g, const StaticOrder& S, const Epi& E, const int tid) {
;     ...
;             PG8_LDB(B0, 0, 0); PG8_LDB(B1, 0, 1); PG8_SCHED; PG8_LDA(At, 0, 0); PG8_STAGE(PG8_SA(1, 1), a1 + hstepA, voffA);
;             PG8_WAIT_V(8); PG8_WAIT_L(0); PG8_BAR; PG8_MMA(0, 0, At, B0); PG8_MMA(0, 1, At, B1); PG8_BAR; PG8_SCHED;
;             PG8_LDA(At, 0, 1); PG8_STAGE(PG8_SB(0, 0), b2, voffB); PG8_STAGE(PG8_SB(0, 1), b2 + hstepB, voffB); PG8_STAGE(PG8_SA(0, 0), a2, voffA);
;             PG8_WAIT_V(8); PG8_WAIT_L(0); PG8_BAR; PG8_MMA(1, 0, At, B0); PG8_MMA(1, 1, At, B1); PG8_BAR; PG8_SCHED;
;             PG8_LDB(B0, 1, 0); PG8_LDB(B1, 1, 1); PG8_SCHED; PG8_LDA(At, 1, 0); PG8_STAGE(PG8_SA(0, 1), a2 + hstepA, voffA);
;             PG8_WAIT_V(8); PG8_WAIT_L(0); PG8_BAR; PG8_MMA(0, 0, At, B0); PG8_MMA(0, 1, At, B1); PG8_BAR; PG8_SCHED;
;             PG8_LDA(At, 1, 1); PG8_STAGE(PG8_SB(1, 0), b3, voffB); PG8_STAGE(PG8_SB(1, 1), b3 + hstepB, voffB); PG8_STAGE(PG8_SA(1, 0), a3, voffA);
;             PG8_WAIT_V(8); PG8_WAIT_L(0); PG8_BAR; PG8_MMA(1, 0, At, B0); PG8_MMA(1, 1, At, B1); PG8_BAR; PG8_SCHED;
.Lkl652_nofa:
	s_waitcnt vmcnt(14)
	s_waitcnt lgkmcnt(0)
	s_barrier
	s_setprio 1
	s_waitcnt lgkmcnt(0)
	v_mfma_f32_16x16x32_bf16 v[110:113], v[130:133], v[162:165], 0
	v_mfma_f32_16x16x32_bf16 v[106:109], v[138:141], v[162:165], 0
	v_mfma_f32_16x16x32_bf16 v[94:97], v[130:133], v[170:173], 0
	v_mfma_f32_16x16x32_bf16 v[90:93], v[138:141], v[170:173], 0
	v_mfma_f32_16x16x32_bf16 v[114:117], v[130:133], v[192:195], 0
	v_mfma_f32_16x16x32_bf16 v[62:65], v[138:141], v[192:195], 0
	v_mfma_f32_16x16x32_bf16 v[126:129], v[130:133], v[210:213], 0
	v_mfma_f32_16x16x32_bf16 v[70:73], v[138:141], v[210:213], 0
	v_mfma_f32_16x16x32_bf16 v[110:113], v[134:137], v[166:169], v[110:113]
	v_mfma_f32_16x16x32_bf16 v[106:109], v[142:145], v[166:169], v[106:109]
	v_mfma_f32_16x16x32_bf16 v[94:97], v[134:137], v[174:177], v[94:97]
	v_mfma_f32_16x16x32_bf16 v[90:93], v[142:145], v[174:177], v[90:93]
	v_mfma_f32_16x16x32_bf16 v[114:117], v[134:137], v[206:209], v[114:117]
	v_mfma_f32_16x16x32_bf16 v[62:65], v[142:145], v[206:209], v[62:65]
	v_mfma_f32_16x16x32_bf16 v[126:129], v[134:137], v[214:217], v[126:129]
	v_mfma_f32_16x16x32_bf16 v[70:73], v[142:145], v[214:217], v[70:73]
	s_setprio 0
	s_setprio 1
	v_mfma_f32_16x16x32_bf16 v[102:105], v[146:149], v[162:165], 0
	v_mfma_f32_16x16x32_bf16 v[98:101], v[154:157], v[162:165], 0
	v_mfma_f32_16x16x32_bf16 v[86:89], v[146:149], v[170:173], 0
	v_mfma_f32_16x16x32_bf16 v[82:85], v[154:157], v[170:173], 0
	v_mfma_f32_16x16x32_bf16 v[118:121], v[146:149], v[192:195], 0
	v_mfma_f32_16x16x32_bf16 v[58:61], v[154:157], v[192:195], 0
	v_mfma_f32_16x16x32_bf16 v[122:125], v[146:149], v[210:213], 0
	v_mfma_f32_16x16x32_bf16 v[66:69], v[154:157], v[210:213], 0
	v_mfma_f32_16x16x32_bf16 v[102:105], v[150:153], v[166:169], v[102:105]
	v_mfma_f32_16x16x32_bf16 v[98:101], v[158:161], v[166:169], v[98:101]
	v_mfma_f32_16x16x32_bf16 v[86:89], v[150:153], v[174:177], v[86:89]
	v_mfma_f32_16x16x32_bf16 v[82:85], v[158:161], v[174:177], v[82:85]
	v_mfma_f32_16x16x32_bf16 v[118:121], v[150:153], v[206:209], v[118:121]
	v_mfma_f32_16x16x32_bf16 v[58:61], v[158:161], v[206:209], v[58:61]
	v_mfma_f32_16x16x32_bf16 v[122:125], v[150:153], v[214:217], v[122:125]
	v_mfma_f32_16x16x32_bf16 v[66:69], v[158:161], v[214:217], v[66:69]
	s_setprio 0
	s_barrier
	s_add_i32 s43, s43, s53
	v_lshl_add_u64 v[178:179], s[44:45], 0, v[182:183]
	s_mov_b32 m0, s43
	ds_read_b128 v[162:165], v205 offset:16384
	ds_read_b128 v[166:169], v205 offset:17408
	ds_read_b128 v[170:173], v205 offset:18432
	ds_read_b128 v[174:177], v205 offset:19456
	ds_read_b128 v[192:195], v205 offset:20480
	ds_read_b128 v[206:209], v205 offset:21504
	ds_read_b128 v[210:213], v205 offset:22528
	ds_read_b128 v[214:217], v205 offset:23552
	global_load_lds_dwordx4 v[178:179], off
	s_add_i32 m0, s43, 0x2000
	v_lshl_add_u64 v[202:203], s[44:45], 0, v[186:187]
	s_add_u32 s44, s44, s12
	s_addc_u32 s45, s45, s13
	s_add_i32 s11, s11, s53
	global_load_lds_dwordx4 v[202:203], off
	v_lshl_add_u64 v[218:219], s[44:45], 0, v[182:183]
	s_mov_b32 m0, s11
	v_lshl_add_u64 v[220:221], s[44:45], 0, v[186:187]
	global_load_lds_dwordx4 v[218:219], off
	s_add_i32 m0, s11, 0x2000
	v_lshl_add_u64 v[222:223], s[8:9], 0, v[180:181]
	global_load_lds_dwordx4 v[220:221], off
	s_mov_b32 m0, s54
	v_lshl_add_u64 v[224:225], s[8:9], 0, v[184:185]
	global_load_lds_dwordx4 v[222:223], off
	s_mov_b32 m0, s55
	s_nop 0
	global_load_lds_dwordx4 v[224:225], off
	s_cmp_eq_u32 s73, 1
	s_cbranch_scc1 .Lkl652_w1f
	s_waitcnt vmcnt(20)
	s_branch .Lkl652_w1j

; #define PG8_STAGE(bufoff, gbase, voff) do { _Pragma("unroll") for (int _i = 0; _i < 2; ++_i) \
;         __builtin_amdgcn_global_load_lds((const unsigned*)((const char*)(gbase) + (voff)[_i]), (LAS unsigned*)(lds + (bufoff) + ldsw + _i * 8192), 16, 0, 0); } while (0)
; #define PG8_LDA(dst, b, h) do { _Pragma("unroll") for (int m = 0; m < 4; ++m) _Pragma("unroll") for (int k = 0; k < 2; ++k) dst[m][k] = *(const LAS bf16x8*)(lds + PG8_SA(b, h) + aoff + m * 2048 + k * 1024); } while (0)
; #define PG8_LDB(dst, b, h) do { _Pragma("unroll") for (int n = 0; n < 2; ++n) _Pragma("unroll") for (int k = 0; k < 2; ++k) dst[n][k] = *(const LAS bf16x8*)(lds + PG8_SB(b, h) + boff + n * 2048 + k * 1024); } while (0)
; #define PG8_MMA(ai, bj, At, Bt) do { __builtin_amdgcn_s_setprio(1); _Pragma("unroll") for (int m = 0; m < 4; ++m) _Pragma("unroll") for (int n = 0; n < 2; ++n) _Pragma("unroll") for (int k = 0; k < 2; ++k) \
;         acc[ai][bj][m][n] = __builtin_amdgcn_mfma_f32_16x16x32_bf16(Bt[n][k], At[m][k], acc[ai][bj][m][n], 0, 0, 0); __builtin_amdgcn_s_setprio(0); } while (0)
; #define PG8_WAIT_V(n) asm volatile("s_waitcnt vmcnt(" #n ")" ::: "memory")
; #define PG8_BAR __builtin_amdgcn_s_barrier()
; template <class Epi>
; __device__ __forceinline__ void gemm_phase(LAS unsigned char* lds, const Gemm g, const StaticOrder& S, const Epi& E, const int tid) {
;     ...
;             PG8_LDB(B0, 0, 0); PG8_LDB(B1, 0, 1); PG8_SCHED; PG8_LDA(At, 0, 0); PG8_STAGE(PG8_SA(1, 1), a1 + hstepA, voffA);
;             PG8_WAIT_V(8); PG8_WAIT_L(0); PG8_BAR; PG8_MMA(0, 0, At, B0); PG8_MMA(0, 1, At, B1); PG8_BAR; PG8_SCHED;
;             PG8_LDA(At, 0, 1); PG8_STAGE(PG8_SB(0, 0), b2, voffB); PG8_STAGE(PG8_SB(0, 1), b2 + hstepB, voffB); PG8_STAGE(PG8_SA(0, 0), a2, voffA);
;             PG8_WAIT_V(8); PG8_WAIT_L(0); PG8_BAR; PG8_MMA(1, 0, At, B0); PG8_MMA(1, 1, At, B1); PG8_BAR; PG8_SCHED;
;             PG8_LDB(B0, 1, 0); PG8_LDB(B1, 1, 1); PG8_SCHED; PG8_LDA(At, 1, 0); PG8_STAGE(PG8_SA(0, 1), a2 + hstepA, voffA);
;             PG8_WAIT_V(8); PG8_WAIT_L(0); PG8_BAR; PG8_MMA(0, 0, At, B0); PG8_MMA(0, 1, At, B1); PG8_BAR; PG8_SCHED;
;             PG8_LDA(At, 1, 1); PG8_STAGE(PG8_SB(1, 0), b3, voffB); PG8_STAGE(PG8_SB(1, 1), b3 + hstepB, voffB); PG8_STAGE(PG8_SA(1, 0), a3, voffA);
;             PG8_WAIT_V(8); PG8_WAIT_L(0); PG8_BAR; PG8_MMA(1, 0, At, B0); PG8_MMA(1, 1, At, B1); PG8_BAR; PG8_SCHED;
.Lkl652_w1j:
	s_waitcnt lgkmcnt(0)
	s_barrier
	s_setprio 1
	s_waitcnt lgkmcnt(0)
	v_mfma_f32_16x16x32_bf16 v[46:49], v[130:133], v[162:165], 0
	v_mfma_f32_16x16x32_bf16 v[30:33], v[138:141], v[162:165], 0
	v_mfma_f32_16x16x32_bf16 v[38:41], v[130:133], v[170:173], 0
	v_mfma_f32_16x16x32_bf16 v[18:21], v[138:141], v[170:173], 0
	v_mfma_f32_16x16x32_bf16 v[50:53], v[130:133], v[192:195], 0
	v_mfma_f32_16x16x32_bf16 v[2:5], v[138:141], v[192:195], 0
	v_mfma_f32_16x16x32_bf16 v[74:77], v[130:133], v[210:213], 0
	v_mfma_f32_16x16x32_bf16 v[10:13], v[138:141], v[210:213], 0
	v_mfma_f32_16x16x32_bf16 v[46:49], v[134:137], v[166:169], v[46:49]
	v_mfma_f32_16x16x32_bf16 v[30:33], v[142:145], v[166:169], v[30:33]
	v_mfma_f32_16x16x32_bf16 v[38:41], v[134:137], v[174:177], v[38:41]
	v_mfma_f32_16x16x32_bf16 v[18:21], v[142:145], v[174:177], v[18:21]
	v_mfma_f32_16x16x32_bf16 v[50:53], v[134:137], v[206:209], v[50:53]
	v_mfma_f32_16x16x32_bf16 v[2:5], v[142:145], v[206:209], v[2:5]
	v_mfma_f32_16x16x32_bf16 v[74:77], v[134:137], v[214:217], v[74:77]
	v_mfma_f32_16x16x32_bf16 v[10:13], v[142:145], v[214:217], v[10:13]
	s_setprio 0
	s_setprio 1
	v_mfma_f32_16x16x32_bf16 v[42:45], v[146:149], v[162:165], 0
	v_mfma_f32_16x16x32_bf16 v[34:37], v[154:157], v[162:165], 0
	v_mfma_f32_16x16x32_bf16 v[26:29], v[146:149], v[170:173], 0
	v_mfma_f32_16x16x32_bf16 v[22:25], v[154:157], v[170:173], 0
	v_mfma_f32_16x16x32_bf16 v[54:57], v[146:149], v[192:195], 0
	v_mfma_f32_16x16x32_bf16 v[6:9], v[154:157], v[192:195], 0
	v_mfma_f32_16x16x32_bf16 v[78:81], v[146:149], v[210:213], 0
	v_mfma_f32_16x16x32_bf16 v[14:17], v[154:157], v[210:213], 0
	v_mfma_f32_16x16x32_bf16 v[42:45], v[150:153], v[166:169], v[42:45]
	v_mfma_f32_16x16x32_bf16 v[34:37], v[158:161], v[166:169], v[34:37]
	v_mfma_f32_16x16x32_bf16 v[26:29], v[150:153], v[174:177], v[26:29]
	v_mfma_f32_16x16x32_bf16 v[22:25], v[158:161], v[174:177], v[22:25]
	v_mfma_f32_16x16x32_bf16 v[54:57], v[150:153], v[206:209], v[54:57]
	v_mfma_f32_16x16x32_bf16 v[6:9], v[158:161], v[206:209], v[6:9]
	v_mfma_f32_16x16x32_bf16 v[78:81], v[150:153], v[214:217], v[78:81]
	v_mfma_f32_16x16x32_bf16 v[14:17], v[158:161], v[214:217], v[14:17]
	s_setprio 0
	s_barrier
	s_add_i32 s11, 0, 0x18000
	v_add_u32_e32 v0, s11, v204
	s_add_i32 s43, 0, 0x1c000
	ds_read_b128 v[130:133], v0
	ds_read_b128 v[134:137], v0 offset:1024
	ds_read_b128 v[138:141], v0 offset:2048
	ds_read_b128 v[142:145], v0 offset:3072
	v_add_u32_e32 v0, s43, v204
	ds_read_b128 v[146:149], v0
	ds_read_b128 v[150:153], v0 offset:1024
	ds_read_b128 v[154:157], v0 offset:2048
	ds_read_b128 v[158:161], v0 offset:3072
	s_add_u32 s8, s8, s0
	s_addc_u32 s9, s9, s1
	s_mov_b32 m0, s56
	v_lshl_add_u64 v[226:227], s[8:9], 0, v[180:181]
	ds_read_b128 v[162:165], v205 offset:32768
	ds_read_b128 v[166:169], v205 offset:33792
	ds_read_b128 v[170:173], v205 offset:34816
	ds_read_b128 v[174:177], v205 offset:35840
	ds_read_b128 v[192:195], v205 offset:36864
	ds_read_b128 v[206:209], v205 offset:37888
	ds_read_b128 v[210:213], v205 offset:38912
	ds_read_b128 v[214:217], v205 offset:39936
	global_load_lds_dwordx4 v[226:227], off
	v_lshl_add_u64 v[226:227], s[8:9], 0, v[184:185]
	s_mov_b32 m0, s57
	s_nop 0
	global_load_lds_dwordx4 v[226:227], off
	s_cmp_eq_u32 s73, 1
	s_cbranch_scc1 .Lkl652_w2f
	s_waitcnt vmcnt(20)
	s_branch .Lkl652_w2j

; #define LAS __attribute__((address_space(3)))
; __device__ __forceinline__ int lane_id_hw() { int l; asm volatile("v_mbcnt_lo_u32_b32 %0, -1, 0\n\tv_mbcnt_hi_u32_b32 %0, -1, %0" : "=v"(l)); return l; }
; __device__ __forceinline__ float sum16(const float* p) { const f32x4 a = *(const f32x4*)p, b = *(const f32x4*)(p + 4), c = *(const f32x4*)(p + 8), d = *(const f32x4*)(p + 12);
;     return ((a[0] + a[1]) + (a[2] + a[3])) + ((b[0] + b[1]) + (b[2] + b[3])) + (((c[0] + c[1]) + (c[2] + c[3])) + ((d[0] + d[1]) + (d[2] + d[3]))); }
;     __device__ __forceinline__ void operator()(f32x4 (&acc)[2][2][4][2], const Unit& u, int wr, int wc, int fr, int fq, int next_pn) const {
;     ...
;         if (*(volatile LAS int*)(R + 256) != u.pm) {
;             const int wv = 4 * wr + wc, l_ = lane_id_hw(); if (wv < 4) { const int r = wv * 64 + l_; R[r] = rsqrtf(sum16(ss + (size_t)(u.pm * BM + r) * 16) * (1.0f / 1024.0f) + EPS); }
;             asm volatile("s_waitcnt lgkmcnt(0)" ::: "memory"); __builtin_amdgcn_s_barrier(); asm volatile("" ::: "memory");
;             if (wv == 0 && l_ == 0) *(volatile LAS int*)(R + 256) = u.pm; }
.LBB0_659:
	s_add_i32 s11, 0, 0x22000
	v_mov_b32_e32 v0, s11
	ds_read_b32 v0, v0
	s_waitcnt lgkmcnt(0)
	v_cmp_eq_u32_e32 vcc, s89, v0
	s_cbranch_vccnz .LBB0_665
	s_andn2_b64 vcc, exec, s[28:29]
	v_mbcnt_lo_u32_b32 v0, -1, 0
	v_mbcnt_hi_u32_b32 v0, -1, v0
	s_cbranch_vccnz .LBB0_662
	v_add_u32_e32 v150, s69, v0
	v_lshl_add_u32 v130, s89, 8, v150
	v_ashrrev_i32_e32 v131, 31, v130
	v_readlane_b32 s8, v254, 51
	v_lshlrev_b64 v[130:131], 6, v[130:131]
	v_readlane_b32 s9, v254, 52
	s_nop 1
	v_lshl_add_u64 v[144:145], s[8:9], 0, v[130:131]
	s_waitcnt lgkmcnt(0)
	v_mov_b32_e32 v130, v228
	v_mov_b32_e32 v131, v229
	v_mov_b32_e32 v132, v230
	v_mov_b32_e32 v133, v231
	v_mov_b32_e32 v134, v232
	v_mov_b32_e32 v135, v233
	v_mov_b32_e32 v136, v234
	v_mov_b32_e32 v137, v235
	v_mov_b32_e32 v140, v236
	v_mov_b32_e32 v141, v237
	v_mov_b32_e32 v142, v238
	v_mov_b32_e32 v143, v239
	v_mov_b32_e32 v144, v196
	v_mov_b32_e32 v145, v197
	v_mov_b32_e32 v146, v198
	v_mov_b32_e32 v147, v199
	v_mov_b32_e32 v148, v130
	v_mov_b32_e32 v149, v134
	v_mov_b32_e32 v134, v131
	v_mov_b32_e32 v130, v132
	v_mov_b32_e32 v131, v136
	v_mov_b32_e32 v136, v133
	v_mov_b32_e32 v132, v140
	v_mov_b32_e32 v133, v144
	v_mov_b32_e32 v144, v141
	v_mov_b32_e32 v140, v142
	v_mov_b32_e32 v141, v146
	v_mov_b32_e32 v146, v143
	v_pk_add_f32 v[134:135], v[148:149], v[134:135]
	v_pk_add_f32 v[130:131], v[130:131], v[136:137]
	v_pk_add_f32 v[132:133], v[132:133], v[144:145]
	v_pk_add_f32 v[136:137], v[140:141], v[146:147]
	v_pk_add_f32 v[130:131], v[134:135], v[130:131]
	v_pk_add_f32 v[132:133], v[132:133], v[136:137]
	s_nop 0
	v_pk_add_f32 v[130:131], v[130:131], v[132:133]
	s_nop 0
	v_add_f32_e32 v130, v130, v131
	v_fmamk_f32 v130, v130, 0x3a800000, v240
	v_mul_f32_e32 v131, 0x4b800000, v130
	v_cmp_gt_f32_e32 vcc, s96, v130
	s_nop 1
	v_cndmask_b32_e32 v130, v130, v131, vcc
	v_rsq_f32_e32 v130, v130
	v_lshl_add_u32 v131, v150, 2, 0
	v_add_u32_e32 v131, 0x21c00, v131
	v_mul_f32_e32 v132, 0x45800000, v130
	v_cndmask_b32_e32 v130, v130, v132, vcc
	ds_write_b32 v131, v130
